# v2 + P0 modvec preamble: the 36 per-thread conditioning-vector loads issued together instead of one load per vmcnt(0) round trip
# baseline (speedup 1.0000x reference)
; __device__ __forceinline__ void p0_modvec(const Params& p, LAS unsigned char* lds, int tid, int lane, int wave) {
;     ...
;     for (int i = tid; i < 9 * 2048; i += 512) { const float v = i < 8 * 2048 ? c[i] : cc[i - 8 * 2048]; svT[(i & 2047) * 12 + (i >> 11)] = v / (1.0f + __expf(-v)); }
.LBB0_12:
	v_lshlrev_b32_e32 v6, 2, v0
	v_mul_u32_u24_e32 v7, 48, v0
	v_add_u32_e32 v8, 0x12000, v7
	global_load_dword v16, v6, s[14:15]
	global_load_dword v17, v6, s[14:15] offset:2048
	s_add_u32 s6, s14, 0x1000
	s_addc_u32 s7, s15, 0
	global_load_dword v18, v6, s[6:7]
	global_load_dword v19, v6, s[6:7] offset:2048
	s_add_u32 s6, s14, 0x2000
	s_addc_u32 s7, s15, 0
	global_load_dword v20, v6, s[6:7]
	global_load_dword v21, v6, s[6:7] offset:2048
	s_add_u32 s6, s14, 0x3000
	s_addc_u32 s7, s15, 0
	global_load_dword v22, v6, s[6:7]
	global_load_dword v23, v6, s[6:7] offset:2048
	s_add_u32 s6, s14, 0x4000
	s_addc_u32 s7, s15, 0
	global_load_dword v24, v6, s[6:7]
	global_load_dword v25, v6, s[6:7] offset:2048
	s_add_u32 s6, s14, 0x5000
	s_addc_u32 s7, s15, 0
	global_load_dword v26, v6, s[6:7]
	global_load_dword v27, v6, s[6:7] offset:2048
	s_add_u32 s6, s14, 0x6000
	s_addc_u32 s7, s15, 0
	global_load_dword v28, v6, s[6:7]
	global_load_dword v29, v6, s[6:7] offset:2048
	s_add_u32 s6, s14, 0x7000
	s_addc_u32 s7, s15, 0
	global_load_dword v30, v6, s[6:7]
	global_load_dword v31, v6, s[6:7] offset:2048
	s_add_u32 s6, s14, 0x8000
	s_addc_u32 s7, s15, 0
	global_load_dword v32, v6, s[6:7]
	global_load_dword v33, v6, s[6:7] offset:2048
	s_add_u32 s6, s14, 0x9000
	s_addc_u32 s7, s15, 0
	global_load_dword v34, v6, s[6:7]
	global_load_dword v35, v6, s[6:7] offset:2048
	s_add_u32 s6, s14, 0xa000
	s_addc_u32 s7, s15, 0
	global_load_dword v36, v6, s[6:7]
	global_load_dword v37, v6, s[6:7] offset:2048
	s_add_u32 s6, s14, 0xb000
	s_addc_u32 s7, s15, 0
	global_load_dword v38, v6, s[6:7]
	global_load_dword v39, v6, s[6:7] offset:2048
	s_add_u32 s6, s14, 0xc000
	s_addc_u32 s7, s15, 0
	global_load_dword v40, v6, s[6:7]
	global_load_dword v41, v6, s[6:7] offset:2048
	s_add_u32 s6, s14, 0xd000
	s_addc_u32 s7, s15, 0
	global_load_dword v42, v6, s[6:7]
	global_load_dword v43, v6, s[6:7] offset:2048
	s_add_u32 s6, s14, 0xe000
	s_addc_u32 s7, s15, 0
	global_load_dword v44, v6, s[6:7]
	global_load_dword v45, v6, s[6:7] offset:2048
	s_add_u32 s6, s14, 0xf000
	s_addc_u32 s7, s15, 0
	global_load_dword v46, v6, s[6:7]
	global_load_dword v47, v6, s[6:7] offset:2048
	global_load_dword v48, v6, s[18:19]
	global_load_dword v49, v6, s[18:19] offset:2048
	s_add_u32 s6, s18, 0x1000
	s_addc_u32 s7, s19, 0
	global_load_dword v50, v6, s[6:7]
	global_load_dword v51, v6, s[6:7] offset:2048
	s_waitcnt vmcnt(35)
	v_mul_f32_e32 v10, 0xbfb8aa3b, v16
	v_exp_f32_e32 v10, v10
	s_nop 0
	v_add_f32_e32 v9, 1.0, v10
	v_div_scale_f32 v10, s[12:13], v9, v9, v16
	v_rcp_f32_e32 v11, v10
	v_div_scale_f32 v12, vcc, v16, v9, v16
	v_fma_f32 v13, -v10, v11, 1.0
	v_fmac_f32_e32 v11, v13, v11
	v_mul_f32_e32 v13, v12, v11
	v_fma_f32 v14, -v10, v13, v12
	v_fmac_f32_e32 v13, v14, v11
	v_fma_f32 v10, -v10, v13, v12
	v_div_fmas_f32 v10, v10, v11, v13
	v_div_fixup_f32 v16, v10, v9, v16
	ds_write_b32 v7, v16 offset:0
	s_waitcnt vmcnt(34)
	v_mul_f32_e32 v10, 0xbfb8aa3b, v17
	v_exp_f32_e32 v10, v10
	s_nop 0
	v_add_f32_e32 v9, 1.0, v10
	v_div_scale_f32 v10, s[12:13], v9, v9, v17
	v_rcp_f32_e32 v11, v10
	v_div_scale_f32 v12, vcc, v17, v9, v17
	v_fma_f32 v13, -v10, v11, 1.0
	v_fmac_f32_e32 v11, v13, v11
	v_mul_f32_e32 v13, v12, v11
	v_fma_f32 v14, -v10, v13, v12
	v_fmac_f32_e32 v13, v14, v11
	v_fma_f32 v10, -v10, v13, v12
	v_div_fmas_f32 v10, v10, v11, v13
	v_div_fixup_f32 v17, v10, v9, v17
	ds_write_b32 v7, v17 offset:24576
	s_waitcnt vmcnt(33)
	v_mul_f32_e32 v10, 0xbfb8aa3b, v18
	v_exp_f32_e32 v10, v10
	s_nop 0
	v_add_f32_e32 v9, 1.0, v10
	v_div_scale_f32 v10, s[12:13], v9, v9, v18
	v_rcp_f32_e32 v11, v10
	v_div_scale_f32 v12, vcc, v18, v9, v18
	v_fma_f32 v13, -v10, v11, 1.0
	v_fmac_f32_e32 v11, v13, v11
	v_mul_f32_e32 v13, v12, v11
	v_fma_f32 v14, -v10, v13, v12
	v_fmac_f32_e32 v13, v14, v11
	v_fma_f32 v10, -v10, v13, v12
	v_div_fmas_f32 v10, v10, v11, v13
	v_div_fixup_f32 v18, v10, v9, v18
	ds_write_b32 v7, v18 offset:49152
	s_waitcnt vmcnt(32)
	v_mul_f32_e32 v10, 0xbfb8aa3b, v19
	v_exp_f32_e32 v10, v10
	s_nop 0
	v_add_f32_e32 v9, 1.0, v10
	v_div_scale_f32 v10, s[12:13], v9, v9, v19
	v_rcp_f32_e32 v11, v10
	v_div_scale_f32 v12, vcc, v19, v9, v19
	v_fma_f32 v13, -v10, v11, 1.0
	v_fmac_f32_e32 v11, v13, v11
	v_mul_f32_e32 v13, v12, v11
	v_fma_f32 v14, -v10, v13, v12
	v_fmac_f32_e32 v13, v14, v11
	v_fma_f32 v10, -v10, v13, v12
	v_div_fmas_f32 v10, v10, v11, v13
	v_div_fixup_f32 v19, v10, v9, v19
	ds_write_b32 v8, v19 offset:0
	s_waitcnt vmcnt(31)
	v_mul_f32_e32 v10, 0xbfb8aa3b, v20
	v_exp_f32_e32 v10, v10
	s_nop 0
	v_add_f32_e32 v9, 1.0, v10
	v_div_scale_f32 v10, s[12:13], v9, v9, v20
	v_rcp_f32_e32 v11, v10
	v_div_scale_f32 v12, vcc, v20, v9, v20
	v_fma_f32 v13, -v10, v11, 1.0
	v_fmac_f32_e32 v11, v13, v11
	v_mul_f32_e32 v13, v12, v11
	v_fma_f32 v14, -v10, v13, v12
	v_fmac_f32_e32 v13, v14, v11
	v_fma_f32 v10, -v10, v13, v12
	v_div_fmas_f32 v10, v10, v11, v13
	v_div_fixup_f32 v20, v10, v9, v20
	ds_write_b32 v7, v20 offset:4
	s_waitcnt vmcnt(30)
	v_mul_f32_e32 v10, 0xbfb8aa3b, v21
	v_exp_f32_e32 v10, v10
	s_nop 0
	v_add_f32_e32 v9, 1.0, v10
	v_div_scale_f32 v10, s[12:13], v9, v9, v21
	v_rcp_f32_e32 v11, v10
	v_div_scale_f32 v12, vcc, v21, v9, v21
	v_fma_f32 v13, -v10, v11, 1.0
	v_fmac_f32_e32 v11, v13, v11
	v_mul_f32_e32 v13, v12, v11
	v_fma_f32 v14, -v10, v13, v12
	v_fmac_f32_e32 v13, v14, v11
	v_fma_f32 v10, -v10, v13, v12
	v_div_fmas_f32 v10, v10, v11, v13
	v_div_fixup_f32 v21, v10, v9, v21
	ds_write_b32 v7, v21 offset:24580
	s_waitcnt vmcnt(29)
; __device__ __forceinline__ void p0_modvec(const Params& p, LAS unsigned char* lds, int tid, int lane, int wave) {
;     ...
;     for (int i = tid; i < 9 * 2048; i += 512) { const float v = i < 8 * 2048 ? c[i] : cc[i - 8 * 2048]; svT[(i & 2047) * 12 + (i >> 11)] = v / (1.0f + __expf(-v)); }
	v_mul_f32_e32 v10, 0xbfb8aa3b, v22
	v_exp_f32_e32 v10, v10
	s_nop 0
	v_add_f32_e32 v9, 1.0, v10
	v_div_scale_f32 v10, s[12:13], v9, v9, v22
	v_rcp_f32_e32 v11, v10
	v_div_scale_f32 v12, vcc, v22, v9, v22
	v_fma_f32 v13, -v10, v11, 1.0
	v_fmac_f32_e32 v11, v13, v11
	v_mul_f32_e32 v13, v12, v11
	v_fma_f32 v14, -v10, v13, v12
	v_fmac_f32_e32 v13, v14, v11
	v_fma_f32 v10, -v10, v13, v12
	v_div_fmas_f32 v10, v10, v11, v13
	v_div_fixup_f32 v22, v10, v9, v22
	ds_write_b32 v7, v22 offset:49156
	s_waitcnt vmcnt(28)
	v_mul_f32_e32 v10, 0xbfb8aa3b, v23
	v_exp_f32_e32 v10, v10
	s_nop 0
	v_add_f32_e32 v9, 1.0, v10
	v_div_scale_f32 v10, s[12:13], v9, v9, v23
	v_rcp_f32_e32 v11, v10
	v_div_scale_f32 v12, vcc, v23, v9, v23
	v_fma_f32 v13, -v10, v11, 1.0
	v_fmac_f32_e32 v11, v13, v11
	v_mul_f32_e32 v13, v12, v11
	v_fma_f32 v14, -v10, v13, v12
	v_fmac_f32_e32 v13, v14, v11
	v_fma_f32 v10, -v10, v13, v12
	v_div_fmas_f32 v10, v10, v11, v13
	v_div_fixup_f32 v23, v10, v9, v23
	ds_write_b32 v8, v23 offset:4
	s_waitcnt vmcnt(27)
	v_mul_f32_e32 v10, 0xbfb8aa3b, v24
	v_exp_f32_e32 v10, v10
	s_nop 0
	v_add_f32_e32 v9, 1.0, v10
	v_div_scale_f32 v10, s[12:13], v9, v9, v24
	v_rcp_f32_e32 v11, v10
	v_div_scale_f32 v12, vcc, v24, v9, v24
	v_fma_f32 v13, -v10, v11, 1.0
	v_fmac_f32_e32 v11, v13, v11
	v_mul_f32_e32 v13, v12, v11
	v_fma_f32 v14, -v10, v13, v12
	v_fmac_f32_e32 v13, v14, v11
	v_fma_f32 v10, -v10, v13, v12
	v_div_fmas_f32 v10, v10, v11, v13
	v_div_fixup_f32 v24, v10, v9, v24
	ds_write_b32 v7, v24 offset:8
	s_waitcnt vmcnt(26)
	v_mul_f32_e32 v10, 0xbfb8aa3b, v25
	v_exp_f32_e32 v10, v10
	s_nop 0
	v_add_f32_e32 v9, 1.0, v10
	v_div_scale_f32 v10, s[12:13], v9, v9, v25
	v_rcp_f32_e32 v11, v10
	v_div_scale_f32 v12, vcc, v25, v9, v25
	v_fma_f32 v13, -v10, v11, 1.0
	v_fmac_f32_e32 v11, v13, v11
	v_mul_f32_e32 v13, v12, v11
	v_fma_f32 v14, -v10, v13, v12
	v_fmac_f32_e32 v13, v14, v11
	v_fma_f32 v10, -v10, v13, v12
	v_div_fmas_f32 v10, v10, v11, v13
	v_div_fixup_f32 v25, v10, v9, v25
	ds_write_b32 v7, v25 offset:24584
	s_waitcnt vmcnt(25)
	v_mul_f32_e32 v10, 0xbfb8aa3b, v26
	v_exp_f32_e32 v10, v10
	s_nop 0
	v_add_f32_e32 v9, 1.0, v10
	v_div_scale_f32 v10, s[12:13], v9, v9, v26
	v_rcp_f32_e32 v11, v10
	v_div_scale_f32 v12, vcc, v26, v9, v26
	v_fma_f32 v13, -v10, v11, 1.0
	v_fmac_f32_e32 v11, v13, v11
	v_mul_f32_e32 v13, v12, v11
	v_fma_f32 v14, -v10, v13, v12
	v_fmac_f32_e32 v13, v14, v11
	v_fma_f32 v10, -v10, v13, v12
	v_div_fmas_f32 v10, v10, v11, v13
	v_div_fixup_f32 v26, v10, v9, v26
	ds_write_b32 v7, v26 offset:49160
	s_waitcnt vmcnt(24)
	v_mul_f32_e32 v10, 0xbfb8aa3b, v27
	v_exp_f32_e32 v10, v10
	s_nop 0
	v_add_f32_e32 v9, 1.0, v10
	v_div_scale_f32 v10, s[12:13], v9, v9, v27
	v_rcp_f32_e32 v11, v10
	v_div_scale_f32 v12, vcc, v27, v9, v27
	v_fma_f32 v13, -v10, v11, 1.0
	v_fmac_f32_e32 v11, v13, v11
	v_mul_f32_e32 v13, v12, v11
	v_fma_f32 v14, -v10, v13, v12
	v_fmac_f32_e32 v13, v14, v11
	v_fma_f32 v10, -v10, v13, v12
	v_div_fmas_f32 v10, v10, v11, v13
	v_div_fixup_f32 v27, v10, v9, v27
	ds_write_b32 v8, v27 offset:8
	s_waitcnt vmcnt(23)
	v_mul_f32_e32 v10, 0xbfb8aa3b, v28
	v_exp_f32_e32 v10, v10
	s_nop 0
	v_add_f32_e32 v9, 1.0, v10
	v_div_scale_f32 v10, s[12:13], v9, v9, v28
	v_rcp_f32_e32 v11, v10
	v_div_scale_f32 v12, vcc, v28, v9, v28
	v_fma_f32 v13, -v10, v11, 1.0
	v_fmac_f32_e32 v11, v13, v11
	v_mul_f32_e32 v13, v12, v11
	v_fma_f32 v14, -v10, v13, v12
	v_fmac_f32_e32 v13, v14, v11
	v_fma_f32 v10, -v10, v13, v12
	v_div_fmas_f32 v10, v10, v11, v13
	v_div_fixup_f32 v28, v10, v9, v28
	ds_write_b32 v7, v28 offset:12
	s_waitcnt vmcnt(22)
	v_mul_f32_e32 v10, 0xbfb8aa3b, v29
	v_exp_f32_e32 v10, v10
	s_nop 0
	v_add_f32_e32 v9, 1.0, v10
	v_div_scale_f32 v10, s[12:13], v9, v9, v29
	v_rcp_f32_e32 v11, v10
	v_div_scale_f32 v12, vcc, v29, v9, v29
	v_fma_f32 v13, -v10, v11, 1.0
	v_fmac_f32_e32 v11, v13, v11
	v_mul_f32_e32 v13, v12, v11
	v_fma_f32 v14, -v10, v13, v12
	v_fmac_f32_e32 v13, v14, v11
	v_fma_f32 v10, -v10, v13, v12
	v_div_fmas_f32 v10, v10, v11, v13
	v_div_fixup_f32 v29, v10, v9, v29
	ds_write_b32 v7, v29 offset:24588
	s_waitcnt vmcnt(21)
	v_mul_f32_e32 v10, 0xbfb8aa3b, v30
	v_exp_f32_e32 v10, v10
	s_nop 0
	v_add_f32_e32 v9, 1.0, v10
	v_div_scale_f32 v10, s[12:13], v9, v9, v30
	v_rcp_f32_e32 v11, v10
	v_div_scale_f32 v12, vcc, v30, v9, v30
	v_fma_f32 v13, -v10, v11, 1.0
	v_fmac_f32_e32 v11, v13, v11
	v_mul_f32_e32 v13, v12, v11
	v_fma_f32 v14, -v10, v13, v12
	v_fmac_f32_e32 v13, v14, v11
	v_fma_f32 v10, -v10, v13, v12
	v_div_fmas_f32 v10, v10, v11, v13
	v_div_fixup_f32 v30, v10, v9, v30
	ds_write_b32 v7, v30 offset:49164
	s_waitcnt vmcnt(20)
	v_mul_f32_e32 v10, 0xbfb8aa3b, v31
	v_exp_f32_e32 v10, v10
	s_nop 0
	v_add_f32_e32 v9, 1.0, v10
	v_div_scale_f32 v10, s[12:13], v9, v9, v31
	v_rcp_f32_e32 v11, v10
	v_div_scale_f32 v12, vcc, v31, v9, v31
	v_fma_f32 v13, -v10, v11, 1.0
	v_fmac_f32_e32 v11, v13, v11
	v_mul_f32_e32 v13, v12, v11
	v_fma_f32 v14, -v10, v13, v12
	v_fmac_f32_e32 v13, v14, v11
	v_fma_f32 v10, -v10, v13, v12
	v_div_fmas_f32 v10, v10, v11, v13
	v_div_fixup_f32 v31, v10, v9, v31
	ds_write_b32 v8, v31 offset:12
	s_waitcnt vmcnt(19)
	v_mul_f32_e32 v10, 0xbfb8aa3b, v32
	v_exp_f32_e32 v10, v10
	s_nop 0
	v_add_f32_e32 v9, 1.0, v10
	v_div_scale_f32 v10, s[12:13], v9, v9, v32
	v_rcp_f32_e32 v11, v10
	v_div_scale_f32 v12, vcc, v32, v9, v32
	v_fma_f32 v13, -v10, v11, 1.0
	v_fmac_f32_e32 v11, v13, v11
	v_mul_f32_e32 v13, v12, v11
	v_fma_f32 v14, -v10, v13, v12
	v_fmac_f32_e32 v13, v14, v11
	v_fma_f32 v10, -v10, v13, v12
	v_div_fmas_f32 v10, v10, v11, v13
	v_div_fixup_f32 v32, v10, v9, v32
	ds_write_b32 v7, v32 offset:16
	s_waitcnt vmcnt(18)
; __device__ __forceinline__ void p0_modvec(const Params& p, LAS unsigned char* lds, int tid, int lane, int wave) {
;     ...
;     for (int i = tid; i < 9 * 2048; i += 512) { const float v = i < 8 * 2048 ? c[i] : cc[i - 8 * 2048]; svT[(i & 2047) * 12 + (i >> 11)] = v / (1.0f + __expf(-v)); }
	v_mul_f32_e32 v10, 0xbfb8aa3b, v33
	v_exp_f32_e32 v10, v10
	s_nop 0
	v_add_f32_e32 v9, 1.0, v10
	v_div_scale_f32 v10, s[12:13], v9, v9, v33
	v_rcp_f32_e32 v11, v10
	v_div_scale_f32 v12, vcc, v33, v9, v33
	v_fma_f32 v13, -v10, v11, 1.0
	v_fmac_f32_e32 v11, v13, v11
	v_mul_f32_e32 v13, v12, v11
	v_fma_f32 v14, -v10, v13, v12
	v_fmac_f32_e32 v13, v14, v11
	v_fma_f32 v10, -v10, v13, v12
	v_div_fmas_f32 v10, v10, v11, v13
	v_div_fixup_f32 v33, v10, v9, v33
	ds_write_b32 v7, v33 offset:24592
	s_waitcnt vmcnt(17)
	v_mul_f32_e32 v10, 0xbfb8aa3b, v34
	v_exp_f32_e32 v10, v10
	s_nop 0
	v_add_f32_e32 v9, 1.0, v10
	v_div_scale_f32 v10, s[12:13], v9, v9, v34
	v_rcp_f32_e32 v11, v10
	v_div_scale_f32 v12, vcc, v34, v9, v34
	v_fma_f32 v13, -v10, v11, 1.0
	v_fmac_f32_e32 v11, v13, v11
	v_mul_f32_e32 v13, v12, v11
	v_fma_f32 v14, -v10, v13, v12
	v_fmac_f32_e32 v13, v14, v11
	v_fma_f32 v10, -v10, v13, v12
	v_div_fmas_f32 v10, v10, v11, v13
	v_div_fixup_f32 v34, v10, v9, v34
	ds_write_b32 v7, v34 offset:49168
	s_waitcnt vmcnt(16)
	v_mul_f32_e32 v10, 0xbfb8aa3b, v35
	v_exp_f32_e32 v10, v10
	s_nop 0
	v_add_f32_e32 v9, 1.0, v10
	v_div_scale_f32 v10, s[12:13], v9, v9, v35
	v_rcp_f32_e32 v11, v10
	v_div_scale_f32 v12, vcc, v35, v9, v35
	v_fma_f32 v13, -v10, v11, 1.0
	v_fmac_f32_e32 v11, v13, v11
	v_mul_f32_e32 v13, v12, v11
	v_fma_f32 v14, -v10, v13, v12
	v_fmac_f32_e32 v13, v14, v11
	v_fma_f32 v10, -v10, v13, v12
	v_div_fmas_f32 v10, v10, v11, v13
	v_div_fixup_f32 v35, v10, v9, v35
	ds_write_b32 v8, v35 offset:16
	s_waitcnt vmcnt(15)
	v_mul_f32_e32 v10, 0xbfb8aa3b, v36
	v_exp_f32_e32 v10, v10
	s_nop 0
	v_add_f32_e32 v9, 1.0, v10
	v_div_scale_f32 v10, s[12:13], v9, v9, v36
	v_rcp_f32_e32 v11, v10
	v_div_scale_f32 v12, vcc, v36, v9, v36
	v_fma_f32 v13, -v10, v11, 1.0
	v_fmac_f32_e32 v11, v13, v11
	v_mul_f32_e32 v13, v12, v11
	v_fma_f32 v14, -v10, v13, v12
	v_fmac_f32_e32 v13, v14, v11
	v_fma_f32 v10, -v10, v13, v12
	v_div_fmas_f32 v10, v10, v11, v13
	v_div_fixup_f32 v36, v10, v9, v36
	ds_write_b32 v7, v36 offset:20
	s_waitcnt vmcnt(14)
	v_mul_f32_e32 v10, 0xbfb8aa3b, v37
	v_exp_f32_e32 v10, v10
	s_nop 0
	v_add_f32_e32 v9, 1.0, v10
	v_div_scale_f32 v10, s[12:13], v9, v9, v37
	v_rcp_f32_e32 v11, v10
	v_div_scale_f32 v12, vcc, v37, v9, v37
	v_fma_f32 v13, -v10, v11, 1.0
	v_fmac_f32_e32 v11, v13, v11
	v_mul_f32_e32 v13, v12, v11
	v_fma_f32 v14, -v10, v13, v12
	v_fmac_f32_e32 v13, v14, v11
	v_fma_f32 v10, -v10, v13, v12
	v_div_fmas_f32 v10, v10, v11, v13
	v_div_fixup_f32 v37, v10, v9, v37
	ds_write_b32 v7, v37 offset:24596
	s_waitcnt vmcnt(13)
	v_mul_f32_e32 v10, 0xbfb8aa3b, v38
	v_exp_f32_e32 v10, v10
	s_nop 0
	v_add_f32_e32 v9, 1.0, v10
	v_div_scale_f32 v10, s[12:13], v9, v9, v38
	v_rcp_f32_e32 v11, v10
	v_div_scale_f32 v12, vcc, v38, v9, v38
	v_fma_f32 v13, -v10, v11, 1.0
	v_fmac_f32_e32 v11, v13, v11
	v_mul_f32_e32 v13, v12, v11
	v_fma_f32 v14, -v10, v13, v12
	v_fmac_f32_e32 v13, v14, v11
	v_fma_f32 v10, -v10, v13, v12
	v_div_fmas_f32 v10, v10, v11, v13
	v_div_fixup_f32 v38, v10, v9, v38
	ds_write_b32 v7, v38 offset:49172
	s_waitcnt vmcnt(12)
	v_mul_f32_e32 v10, 0xbfb8aa3b, v39
	v_exp_f32_e32 v10, v10
	s_nop 0
	v_add_f32_e32 v9, 1.0, v10
	v_div_scale_f32 v10, s[12:13], v9, v9, v39
	v_rcp_f32_e32 v11, v10
	v_div_scale_f32 v12, vcc, v39, v9, v39
	v_fma_f32 v13, -v10, v11, 1.0
	v_fmac_f32_e32 v11, v13, v11
	v_mul_f32_e32 v13, v12, v11
	v_fma_f32 v14, -v10, v13, v12
	v_fmac_f32_e32 v13, v14, v11
	v_fma_f32 v10, -v10, v13, v12
	v_div_fmas_f32 v10, v10, v11, v13
	v_div_fixup_f32 v39, v10, v9, v39
	ds_write_b32 v8, v39 offset:20
	s_waitcnt vmcnt(11)
	v_mul_f32_e32 v10, 0xbfb8aa3b, v40
	v_exp_f32_e32 v10, v10
	s_nop 0
	v_add_f32_e32 v9, 1.0, v10
	v_div_scale_f32 v10, s[12:13], v9, v9, v40
	v_rcp_f32_e32 v11, v10
	v_div_scale_f32 v12, vcc, v40, v9, v40
	v_fma_f32 v13, -v10, v11, 1.0
	v_fmac_f32_e32 v11, v13, v11
	v_mul_f32_e32 v13, v12, v11
	v_fma_f32 v14, -v10, v13, v12
	v_fmac_f32_e32 v13, v14, v11
	v_fma_f32 v10, -v10, v13, v12
	v_div_fmas_f32 v10, v10, v11, v13
	v_div_fixup_f32 v40, v10, v9, v40
	ds_write_b32 v7, v40 offset:24
	s_waitcnt vmcnt(10)
	v_mul_f32_e32 v10, 0xbfb8aa3b, v41
	v_exp_f32_e32 v10, v10
	s_nop 0
	v_add_f32_e32 v9, 1.0, v10
	v_div_scale_f32 v10, s[12:13], v9, v9, v41
	v_rcp_f32_e32 v11, v10
	v_div_scale_f32 v12, vcc, v41, v9, v41
	v_fma_f32 v13, -v10, v11, 1.0
	v_fmac_f32_e32 v11, v13, v11
	v_mul_f32_e32 v13, v12, v11
	v_fma_f32 v14, -v10, v13, v12
	v_fmac_f32_e32 v13, v14, v11
	v_fma_f32 v10, -v10, v13, v12
	v_div_fmas_f32 v10, v10, v11, v13
	v_div_fixup_f32 v41, v10, v9, v41
	ds_write_b32 v7, v41 offset:24600
	s_waitcnt vmcnt(9)
	v_mul_f32_e32 v10, 0xbfb8aa3b, v42
	v_exp_f32_e32 v10, v10
	s_nop 0
	v_add_f32_e32 v9, 1.0, v10
	v_div_scale_f32 v10, s[12:13], v9, v9, v42
	v_rcp_f32_e32 v11, v10
	v_div_scale_f32 v12, vcc, v42, v9, v42
	v_fma_f32 v13, -v10, v11, 1.0
	v_fmac_f32_e32 v11, v13, v11
	v_mul_f32_e32 v13, v12, v11
	v_fma_f32 v14, -v10, v13, v12
	v_fmac_f32_e32 v13, v14, v11
	v_fma_f32 v10, -v10, v13, v12
	v_div_fmas_f32 v10, v10, v11, v13
	v_div_fixup_f32 v42, v10, v9, v42
	ds_write_b32 v7, v42 offset:49176
	s_waitcnt vmcnt(8)
	v_mul_f32_e32 v10, 0xbfb8aa3b, v43
	v_exp_f32_e32 v10, v10
	s_nop 0
	v_add_f32_e32 v9, 1.0, v10
	v_div_scale_f32 v10, s[12:13], v9, v9, v43
	v_rcp_f32_e32 v11, v10
	v_div_scale_f32 v12, vcc, v43, v9, v43
	v_fma_f32 v13, -v10, v11, 1.0
	v_fmac_f32_e32 v11, v13, v11
	v_mul_f32_e32 v13, v12, v11
	v_fma_f32 v14, -v10, v13, v12
	v_fmac_f32_e32 v13, v14, v11
	v_fma_f32 v10, -v10, v13, v12
	v_div_fmas_f32 v10, v10, v11, v13
	v_div_fixup_f32 v43, v10, v9, v43
	ds_write_b32 v8, v43 offset:24
	s_waitcnt vmcnt(7)
; #define GAS __attribute__((address_space(1)))
; #define LAS __attribute__((address_space(3)))
; __device__ __forceinline__ void p0_modvec(const Params& p, LAS unsigned char* lds, int tid, int lane, int wave) {
;     ...
;     for (int i = tid; i < 9 * 2048; i += 512) { const float v = i < 8 * 2048 ? c[i] : cc[i - 8 * 2048]; svT[(i & 2047) * 12 + (i >> 11)] = v / (1.0f + __expf(-v)); }
;     float* MOD = (float*)(p.ws + WS_MOD);
;     const int ln = lane & 15, lk = lane >> 4;
;     const LAS float* svw = svT + (wave * 256 + lk) * 12 + min(ln, 11);
;     for (int u = blockIdx.x; u < 2 * (DMODW / UC); u += gridDim.x) {
;         __syncthreads();
;         const int l = u / (DMODW / UC), col0 = (u % (DMODW / UC)) * UC;
;         const GAS float* Wu = (const GAS float*)uniform_ptr(p.in[IN_WMOD] + (size_t)l * D * DMODW + col0 + (size_t)(wave * 256) * DMODW);
;         const unsigned loff = (unsigned)(lk * DMODW + ln);
	v_mul_f32_e32 v10, 0xbfb8aa3b, v44
	v_exp_f32_e32 v10, v10
	s_nop 0
	v_add_f32_e32 v9, 1.0, v10
	v_div_scale_f32 v10, s[12:13], v9, v9, v44
	v_rcp_f32_e32 v11, v10
	v_div_scale_f32 v12, vcc, v44, v9, v44
	v_fma_f32 v13, -v10, v11, 1.0
	v_fmac_f32_e32 v11, v13, v11
	v_mul_f32_e32 v13, v12, v11
	v_fma_f32 v14, -v10, v13, v12
	v_fmac_f32_e32 v13, v14, v11
	v_fma_f32 v10, -v10, v13, v12
	v_div_fmas_f32 v10, v10, v11, v13
	v_div_fixup_f32 v44, v10, v9, v44
	ds_write_b32 v7, v44 offset:28
	s_waitcnt vmcnt(6)
	v_mul_f32_e32 v10, 0xbfb8aa3b, v45
	v_exp_f32_e32 v10, v10
	s_nop 0
	v_add_f32_e32 v9, 1.0, v10
	v_div_scale_f32 v10, s[12:13], v9, v9, v45
	v_rcp_f32_e32 v11, v10
	v_div_scale_f32 v12, vcc, v45, v9, v45
	v_fma_f32 v13, -v10, v11, 1.0
	v_fmac_f32_e32 v11, v13, v11
	v_mul_f32_e32 v13, v12, v11
	v_fma_f32 v14, -v10, v13, v12
	v_fmac_f32_e32 v13, v14, v11
	v_fma_f32 v10, -v10, v13, v12
	v_div_fmas_f32 v10, v10, v11, v13
	v_div_fixup_f32 v45, v10, v9, v45
	ds_write_b32 v7, v45 offset:24604
	s_waitcnt vmcnt(5)
	v_mul_f32_e32 v10, 0xbfb8aa3b, v46
	v_exp_f32_e32 v10, v10
	s_nop 0
	v_add_f32_e32 v9, 1.0, v10
	v_div_scale_f32 v10, s[12:13], v9, v9, v46
	v_rcp_f32_e32 v11, v10
	v_div_scale_f32 v12, vcc, v46, v9, v46
	v_fma_f32 v13, -v10, v11, 1.0
	v_fmac_f32_e32 v11, v13, v11
	v_mul_f32_e32 v13, v12, v11
	v_fma_f32 v14, -v10, v13, v12
	v_fmac_f32_e32 v13, v14, v11
	v_fma_f32 v10, -v10, v13, v12
	v_div_fmas_f32 v10, v10, v11, v13
	v_div_fixup_f32 v46, v10, v9, v46
	ds_write_b32 v7, v46 offset:49180
	s_waitcnt vmcnt(4)
	v_mul_f32_e32 v10, 0xbfb8aa3b, v47
	v_exp_f32_e32 v10, v10
	s_nop 0
	v_add_f32_e32 v9, 1.0, v10
	v_div_scale_f32 v10, s[12:13], v9, v9, v47
	v_rcp_f32_e32 v11, v10
	v_div_scale_f32 v12, vcc, v47, v9, v47
	v_fma_f32 v13, -v10, v11, 1.0
	v_fmac_f32_e32 v11, v13, v11
	v_mul_f32_e32 v13, v12, v11
	v_fma_f32 v14, -v10, v13, v12
	v_fmac_f32_e32 v13, v14, v11
	v_fma_f32 v10, -v10, v13, v12
	v_div_fmas_f32 v10, v10, v11, v13
	v_div_fixup_f32 v47, v10, v9, v47
	ds_write_b32 v8, v47 offset:28
	s_waitcnt vmcnt(3)
	v_mul_f32_e32 v10, 0xbfb8aa3b, v48
	v_exp_f32_e32 v10, v10
	s_nop 0
	v_add_f32_e32 v9, 1.0, v10
	v_div_scale_f32 v10, s[12:13], v9, v9, v48
	v_rcp_f32_e32 v11, v10
	v_div_scale_f32 v12, vcc, v48, v9, v48
	v_fma_f32 v13, -v10, v11, 1.0
	v_fmac_f32_e32 v11, v13, v11
	v_mul_f32_e32 v13, v12, v11
	v_fma_f32 v14, -v10, v13, v12
	v_fmac_f32_e32 v13, v14, v11
	v_fma_f32 v10, -v10, v13, v12
	v_div_fmas_f32 v10, v10, v11, v13
	v_div_fixup_f32 v48, v10, v9, v48
	ds_write_b32 v7, v48 offset:32
	s_waitcnt vmcnt(2)
	v_mul_f32_e32 v10, 0xbfb8aa3b, v49
	v_exp_f32_e32 v10, v10
	s_nop 0
	v_add_f32_e32 v9, 1.0, v10
	v_div_scale_f32 v10, s[12:13], v9, v9, v49
	v_rcp_f32_e32 v11, v10
	v_div_scale_f32 v12, vcc, v49, v9, v49
	v_fma_f32 v13, -v10, v11, 1.0
	v_fmac_f32_e32 v11, v13, v11
	v_mul_f32_e32 v13, v12, v11
	v_fma_f32 v14, -v10, v13, v12
	v_fmac_f32_e32 v13, v14, v11
	v_fma_f32 v10, -v10, v13, v12
	v_div_fmas_f32 v10, v10, v11, v13
	v_div_fixup_f32 v49, v10, v9, v49
	ds_write_b32 v7, v49 offset:24608
	s_waitcnt vmcnt(1)
	v_mul_f32_e32 v10, 0xbfb8aa3b, v50
	v_exp_f32_e32 v10, v10
	s_nop 0
	v_add_f32_e32 v9, 1.0, v10
	v_div_scale_f32 v10, s[12:13], v9, v9, v50
	v_rcp_f32_e32 v11, v10
	v_div_scale_f32 v12, vcc, v50, v9, v50
	v_fma_f32 v13, -v10, v11, 1.0
	v_fmac_f32_e32 v11, v13, v11
	v_mul_f32_e32 v13, v12, v11
	v_fma_f32 v14, -v10, v13, v12
	v_fmac_f32_e32 v13, v14, v11
	v_fma_f32 v10, -v10, v13, v12
	v_div_fmas_f32 v10, v10, v11, v13
	v_div_fixup_f32 v50, v10, v9, v50
	ds_write_b32 v7, v50 offset:49184
	s_waitcnt vmcnt(0)
	v_mul_f32_e32 v10, 0xbfb8aa3b, v51
	v_exp_f32_e32 v10, v10
	s_nop 0
	v_add_f32_e32 v9, 1.0, v10
	v_div_scale_f32 v10, s[12:13], v9, v9, v51
	v_rcp_f32_e32 v11, v10
	v_div_scale_f32 v12, vcc, v51, v9, v51
	v_fma_f32 v13, -v10, v11, 1.0
	v_fmac_f32_e32 v11, v13, v11
	v_mul_f32_e32 v13, v12, v11
	v_fma_f32 v14, -v10, v13, v12
	v_fmac_f32_e32 v13, v14, v11
	v_fma_f32 v10, -v10, v13, v12
	v_div_fmas_f32 v10, v10, v11, v13
	v_div_fixup_f32 v51, v10, v9, v51
	ds_write_b32 v8, v51 offset:32
	s_or_b64 exec, exec, s[2:3]
	s_cmpk_gt_i32 s86, 0xff
	s_cbranch_scc1 .LBB0_91
	s_add_u32 s33, s88, 0x100000
	s_addc_u32 s62, s89, 0
	v_and_b32_e32 v3, 15, v0
	v_lshrrev_b32_e32 v4, 4, v1
	s_lshl_b32 s2, s10, 8
	v_or_b32_e32 v2, s2, v4
	v_min_u32_e32 v5, 11, v3
	v_mul_lo_u32 v2, v2, 48
	v_lshlrev_b32_e32 v5, 2, v5
	v_add3_u32 v40, 0, v2, v5
	s_mul_hi_u32 s65, s2, 0x12000
	v_lshlrev_b32_e32 v5, 2, v4
	s_mul_i32 s2, s10, 9
	v_mul_u32_u24_e32 v2, 0x4800, v4
	v_cmp_ne_u32_e32 vcc, 3, v4
	v_add_u32_e32 v4, s2, v5
	v_or_b32_e32 v6, 1, v5
	v_or_b32_e32 v7, 2, v5
	v_or_b32_e32 v5, 3, v5
	s_mul_i32 s63, s10, 0x1200000
	s_add_i32 s66, 0, 0x18000
	s_movk_i32 s3, 0x240
	v_cmp_gt_u32_e64 s[10:11], 9, v6
	v_add_u32_e32 v6, s2, v6
	v_cmp_gt_u32_e64 s[6:7], 9, v7
	v_add_u32_e32 v7, s2, v7
	v_cmp_gt_u32_e64 s[8:9], 9, v5
	v_add_u32_e32 v5, s2, v5
	v_or_b32_e32 v2, v2, v3
	v_lshl_add_u32 v3, v3, 2, s66
	v_mul_lo_u32 v4, v4, s3
	v_mul_lo_u32 v6, v6, s3
	v_mul_lo_u32 v7, v7, s3
	v_mul_lo_u32 v5, v5, s3
	s_mov_b32 s64, 0x12000
	v_mov_b32_e32 v39, 0
	v_lshlrev_b32_e32 v38, 2, v2
	v_add_u32_e32 v41, 0x400, v40
	v_add_u32_e32 v42, 0x600, v40
	v_add_u32_e32 v43, 0x800, v40
	v_add_u32_e32 v44, 0xc00, v40
	v_add_u32_e32 v45, 0x1000, v40
	v_add_u32_e32 v46, 0x1200, v40
	v_add_u32_e32 v47, 0x1400, v40
	v_add_u32_e32 v48, 0x1800, v40
	v_add_u32_e32 v49, 0x1c00, v40
	v_add_u32_e32 v50, 0x1e00, v40
	v_add_u32_e32 v51, 0x2000, v40
	v_add_u32_e32 v52, 0x2400, v40
	v_add_u32_e32 v53, 0x2800, v40
	v_add_u32_e32 v54, 0x2a00, v40
	v_add_u32_e32 v55, 0x2c00, v40
	v_add_u32_e32 v56, v3, v4
	v_add_u32_e32 v57, v3, v6
	v_add_u32_e32 v58, v3, v7
	v_add_u32_e32 v59, v3, v5
	s_mov_b32 s67, s86
	s_mov_b64 s[2:3], 0xca8000
	s_mov_b64 s[14:15], 0xcf0000
	s_mov_b64 s[16:17], 0xd38000
	s_mov_b64 s[18:19], 0xd80000
	s_mov_b64 s[20:21], 0xdc8000
	s_mov_b64 s[22:23], 0xe10000
	s_mov_b64 s[24:25], 0xe58000
	s_mov_b64 s[26:27], 0xea0000
	s_mov_b64 s[28:29], 0xee8000
	s_mov_b64 s[30:31], 0xf30000
	s_mov_b64 s[34:35], 0xf78000
	s_mov_b64 s[36:37], 0xfc0000
	s_mov_b64 s[38:39], 0x1008000
	s_mov_b64 s[40:41], 0x1050000
	s_mov_b64 s[42:43], 0x1098000
	s_mov_b64 s[44:45], 0x10e0000
	s_mov_b64 s[46:47], 0x1128000
	s_mov_b64 s[48:49], 0x1170000
	s_mov_b64 s[50:51], 0x11b8000
	s_branch .LBB0_16
